# indexer POST fast path for fully-causal tiles (bitop3 key map, bfe/mad histogram), first tile loads issued before unit-start zero-fill+barrier, duplicate barrier removed
# speedup vs baseline: 1.0676x; 1.0073x over previous
.LBB0_690:
	v_mov_b32_e32 v144, v202
	s_andn2_b64 vcc, exec, s[54:55]
	v_readfirstlane_b32 s60, v144
	s_mov_b64 s[4:5], -1
	s_cbranch_vccnz .LBB0_689
	s_add_i32 s6, s52, 3
	s_ashr_i32 s13, s6, 5
	s_ashr_i32 s51, s50, 31
	s_ashr_i32 s53, s60, 6
	s_lshl_b64 s[6:7], s[50:51], 20
	v_and_b32_e32 v145, 63, v144
	s_add_u32 s6, s40, s6
	s_addc_u32 s7, s41, s7
	v_lshlrev_b32_e32 v132, 4, v145
	s_nop 0
	v_lshl_add_u64 v[156:157], s[6:7], 0, v[132:133]
	s_min_i32 s6, s53, s13
	s_ashr_i32 s7, s6, 31
	s_lshl_b64 s[6:7], s[6:7], 12
	v_lshl_add_u64 v[4:5], v[156:157], 0, s[6:7]
	global_load_dwordx4 v[80:83], v[4:5], off
	global_load_dwordx4 v[76:79], v[4:5], off offset:1024
	global_load_dwordx4 v[72:75], v[4:5], off offset:2048
	global_load_dwordx4 v[68:71], v[4:5], off offset:3072
	s_add_i32 s6, s53, 8
	s_min_i32 s6, s6, s13
	s_ashr_i32 s7, s6, 31
	s_lshl_b64 s[6:7], s[6:7], 12
	v_lshl_add_u64 v[4:5], v[156:157], 0, s[6:7]
	global_load_dwordx4 v[96:99], v[4:5], off
	global_load_dwordx4 v[92:95], v[4:5], off offset:1024
	global_load_dwordx4 v[88:91], v[4:5], off offset:2048
	global_load_dwordx4 v[84:87], v[4:5], off offset:3072
	v_cmp_gt_i32_e64 s[4:5], s67, v144
	v_add_u32_e32 v158, 0xfffffe00, v144
	v_lshl_add_u32 v160, v144, 4, s68
	s_and_saveexec_b64 s[6:7], s[4:5]
	s_cbranch_execz .LBB0_694
	v_add_u32_e32 v1, 0xfffffe00, v144
	v_lshl_add_u32 v3, v144, 4, s68
	s_mov_b64 s[8:9], 0

.LBB0_696:
	s_or_b64 exec, exec, s[6:7]
	s_add_i32 s6, s52, 3
	s_ashr_i32 s13, s6, 5
	s_ashr_i32 s51, s50, 31
	s_and_b32 s14, s13, 0xffffffe0
	s_add_i32 s10, s14, 32
	s_ashr_i32 s53, s60, 6
	s_lshl_b64 s[6:7], s[50:51], 20
	v_and_b32_e32 v145, 63, v144
	v_bfe_u32 v162, v144, 5, 1
	s_add_u32 s6, s40, s6
	v_lshlrev_b32_e32 v163, 1, v162
	s_addc_u32 s7, s41, s7
	v_lshlrev_b32_e32 v132, 4, v145
	v_and_b32_e32 v164, 31, v144
	v_lshlrev_b32_e32 v167, 16, v162
	v_lshl_add_u32 v165, v162, 13, s68
	v_add_u32_e32 v1, s52, v163
	v_lshl_add_u64 v[156:157], s[6:7], 0, v[132:133]
	v_lshl_add_u32 v166, v145, 2, s71
	s_waitcnt lgkmcnt(0)
	s_barrier
	s_waitcnt vmcnt(8)
	v_swap_b32 v135, v36
	v_swap_b32 v137, v38
	v_swap_b32 v139, v40
	v_swap_b32 v141, v42
	v_add_u32_e32 v132, 1, v1
	v_lshlrev_b32_e32 v168, 2, v164
	v_mov_b32_e32 v172, 0x25a00
	s_mov_b32 s16, s53
	s_add_i32 s17, s53, 8
	s_mov_b32 s10, 0
	s_mov_b32 s18, 0x80000000
	s_mov_b32 s11, 0xffff
	s_add_i32 s19, s52, -31
	s_ashr_i32 s19, s19, 5
	v_add_u32_e32 v100, s73, v165
	v_add_u32_e32 v175, v167, v168
	s_mov_b64 exec, 1
	ds_add_rtn_u32 v171, v172, v149
	s_mov_b64 exec, -1
	s_waitcnt lgkmcnt(0)
	v_readfirstlane_b32 s15, v171
	s_mov_b32 s14, -1
	s_branch .Lidx_entry0

.Lidx_lddone0:
.Lidx_entry0:
	s_cmp_gt_i32 s16, s13
	s_cbranch_scc1 .Lidx_exit_prev1
	s_waitcnt vmcnt(7)
	v_mfma_f32_32x32x16_bf16 v[20:35], v[44:47], v[80:83], 0
	s_waitcnt vmcnt(6)
	v_mfma_f32_32x32x16_bf16 v[20:35], v[48:51], v[76:79], v[20:35]
	s_waitcnt vmcnt(5)
	v_mfma_f32_32x32x16_bf16 v[20:35], v[52:55], v[72:75], v[20:35]
	s_waitcnt vmcnt(4)
	v_mfma_f32_32x32x16_bf16 v[20:35], v[56:59], v[68:71], v[20:35]
	s_cmp_lt_i32 s14, 0
	s_cbranch_scc1 .Lidx_nopost0
	s_cmp_gt_i32 s14, s19
	s_cbranch_scc1 .Lidx_edge0
	v_max_i32_e32 v177, 0, v4
	v_max_i32_e32 v176, 0, v12
	v_max_i32_e32 v179, 0, v5
	v_pk_fma_f32 v[176:177], v[134:135], v[176:177], 0 op_sel_hi:[1,1,0]
	v_max_i32_e32 v178, 0, v13
	v_max_i32_e32 v181, 0, v6
	v_max_i32_e32 v180, 0, v14
	v_pk_fma_f32 v[176:177], v[36:37], v[178:179], v[176:177]
	v_lshl_add_u32 v189, s14, 7, v175
	v_pk_fma_f32 v[176:177], v[136:137], v[180:181], v[176:177]
	v_max_i32_e32 v179, 0, v7
	v_max_i32_e32 v178, 0, v15
	v_pk_fma_f32 v[176:177], v[38:39], v[178:179], v[176:177]
	v_max_i32_e32 v179, 0, v8
	v_max_i32_e32 v178, 0, v16
	v_pk_fma_f32 v[176:177], v[138:139], v[178:179], v[176:177]
	v_max_i32_e32 v179, 0, v9
	v_max_i32_e32 v178, 0, v17
	v_pk_fma_f32 v[176:177], v[40:41], v[178:179], v[176:177]
	v_max_i32_e32 v179, 0, v10
	v_max_i32_e32 v178, 0, v18
	v_pk_fma_f32 v[176:177], v[140:141], v[178:179], v[176:177]
	v_max_i32_e32 v179, 0, v11
	v_max_i32_e32 v178, 0, v19
	v_pk_fma_f32 v[176:177], v[42:43], v[178:179], v[176:177]
	s_nop 0
	v_ashrrev_i32_e32 v182, 31, v177
	v_ashrrev_i32_e32 v183, 31, v176
	v_bitop3_b32 v186, v177, v182, s18 bitop3:0x1e
	v_bitop3_b32 v187, v176, v183, s18 bitop3:0x1e
	ds_write2st64_b32 v189, v186, v187 offset1:128
	v_bfe_u32 v190, v186, 22, 10
	v_bfe_u32 v191, v186, 21, 1
	v_lshl_add_u32 v190, v190, 2, v165
	v_mad_u32_u24 v191, v191, s11, 1
	ds_add_u32 v190, v191
	v_bfe_u32 v184, v187, 22, 10
	v_bfe_u32 v185, v187, 21, 1
	v_lshl_add_u32 v184, v184, 2, v100
	v_mad_u32_u24 v185, v185, s11, 1
	ds_add_u32 v184, v185
.Lidx_postdone0:
	s_waitcnt lgkmcnt(3)
	s_branch .Lidx_join0

.Lidx_lddone1:
	s_cmp_gt_i32 s17, s13
	s_cbranch_scc1 .Lidx_exit_prev0
	s_waitcnt vmcnt(7)
	v_mfma_f32_32x32x16_bf16 v[4:19], v[44:47], v[96:99], 0
	s_waitcnt vmcnt(6)
	v_mfma_f32_32x32x16_bf16 v[4:19], v[48:51], v[92:95], v[4:19]
	s_waitcnt vmcnt(5)
	v_mfma_f32_32x32x16_bf16 v[4:19], v[52:55], v[88:91], v[4:19]
	s_waitcnt vmcnt(4)
	v_mfma_f32_32x32x16_bf16 v[4:19], v[56:59], v[84:87], v[4:19]
	s_cmp_gt_i32 s14, s19
	s_cbranch_scc1 .Lidx_edge1
	v_max_i32_e32 v177, 0, v20
	v_max_i32_e32 v176, 0, v28
	v_max_i32_e32 v179, 0, v21
	v_pk_fma_f32 v[176:177], v[134:135], v[176:177], 0 op_sel_hi:[1,1,0]
	v_max_i32_e32 v178, 0, v29
	v_max_i32_e32 v181, 0, v22
	v_max_i32_e32 v180, 0, v30
	v_pk_fma_f32 v[176:177], v[36:37], v[178:179], v[176:177]
	v_lshl_add_u32 v189, s14, 7, v175
	v_pk_fma_f32 v[176:177], v[136:137], v[180:181], v[176:177]
	v_max_i32_e32 v179, 0, v23
	v_max_i32_e32 v178, 0, v31
	v_pk_fma_f32 v[176:177], v[38:39], v[178:179], v[176:177]
	v_max_i32_e32 v179, 0, v24
	v_max_i32_e32 v178, 0, v32
	v_pk_fma_f32 v[176:177], v[138:139], v[178:179], v[176:177]
	v_max_i32_e32 v179, 0, v25
	v_max_i32_e32 v178, 0, v33
	v_pk_fma_f32 v[176:177], v[40:41], v[178:179], v[176:177]
	v_max_i32_e32 v179, 0, v26
	v_max_i32_e32 v178, 0, v34
	v_pk_fma_f32 v[176:177], v[140:141], v[178:179], v[176:177]
	v_max_i32_e32 v179, 0, v27
	v_max_i32_e32 v178, 0, v35
	v_pk_fma_f32 v[176:177], v[42:43], v[178:179], v[176:177]
	s_nop 0
	v_ashrrev_i32_e32 v182, 31, v177
	v_ashrrev_i32_e32 v183, 31, v176
	v_bitop3_b32 v186, v177, v182, s18 bitop3:0x1e
	v_bitop3_b32 v187, v176, v183, s18 bitop3:0x1e
	ds_write2st64_b32 v189, v186, v187 offset1:128
	v_bfe_u32 v190, v186, 22, 10
	v_bfe_u32 v191, v186, 21, 1
	v_lshl_add_u32 v190, v190, 2, v165
	v_mad_u32_u24 v191, v191, s11, 1
	ds_add_u32 v190, v191
	v_bfe_u32 v184, v187, 22, 10
	v_bfe_u32 v185, v187, 21, 1
	v_lshl_add_u32 v184, v184, 2, v100
	v_mad_u32_u24 v185, v185, s11, 1
	ds_add_u32 v184, v185
.Lidx_postdone1:
	s_waitcnt lgkmcnt(3)
	v_readfirstlane_b32 s15, v171
	s_add_i32 s10, s10, 1
	s_cmpk_lt_i32 s10, 0x400
	s_cbranch_scc1 .Lidx_loop
	s_branch .Lidx_done
.Lidx_edge0:
	v_max_i32_e32 v177, 0, v4
	v_max_i32_e32 v176, 0, v12
	v_max_i32_e32 v179, 0, v5
	v_pk_fma_f32 v[176:177], v[134:135], v[176:177], 0 op_sel_hi:[1,1,0]
	v_max_i32_e32 v178, 0, v13
	v_max_i32_e32 v181, 0, v6
	v_max_i32_e32 v180, 0, v14
	v_pk_fma_f32 v[176:177], v[36:37], v[178:179], v[176:177]
	v_lshl_or_b32 v188, s14, 5, v164
	v_pk_fma_f32 v[176:177], v[136:137], v[180:181], v[176:177]
	v_max_i32_e32 v179, 0, v7
	v_max_i32_e32 v178, 0, v15
	v_pk_fma_f32 v[176:177], v[38:39], v[178:179], v[176:177]
	v_max_i32_e32 v179, 0, v8
	v_max_i32_e32 v178, 0, v16
	v_pk_fma_f32 v[176:177], v[138:139], v[178:179], v[176:177]
	v_max_i32_e32 v179, 0, v9
	v_max_i32_e32 v178, 0, v17
	v_pk_fma_f32 v[176:177], v[40:41], v[178:179], v[176:177]
	v_max_i32_e32 v179, 0, v10
	v_max_i32_e32 v178, 0, v18
	v_pk_fma_f32 v[176:177], v[140:141], v[178:179], v[176:177]
	v_max_i32_e32 v179, 0, v11
	v_max_i32_e32 v178, 0, v19
	v_pk_fma_f32 v[176:177], v[42:43], v[178:179], v[176:177]
	s_nop 0
	v_and_b32_e32 v183, 0x7fffffff, v177
	v_and_b32_e32 v182, 0x7fffffff, v176
	v_xor_b32_e32 v185, -1, v177
	v_pk_add_f32 v[182:183], v[182:183], 0 neg_lo:[1,1] neg_hi:[1,1]
	v_cmp_gt_i32_e32 vcc, 0, v177
	v_xor_b32_e32 v184, -1, v176
	s_nop 0
	v_cndmask_b32_e32 v186, v183, v185, vcc
	v_cmp_gt_i32_e32 vcc, 0, v176
	s_nop 1
	v_cndmask_b32_e32 v187, v182, v184, vcc
	v_cmp_le_i32_e32 vcc, v188, v132
	s_nop 1
	v_cndmask_b32_e32 v187, 0, v187, vcc
	v_cmp_le_i32_e32 vcc, v188, v1
	v_lshl_add_u32 v189, s14, 7, v175
	s_nop 0
	v_cndmask_b32_e32 v186, 0, v186, vcc
	ds_write2st64_b32 v189, v186, v187 offset1:128
	v_lshrrev_b32_e32 v190, 20, v186
	v_cmp_eq_u32_e32 vcc, 0, v186
	v_lshrrev_b32_e32 v191, 17, v186
	v_and_b32_e32 v190, 0xffc, v190
	v_and_b32_e32 v191, 16, v191
	v_add_u32_e32 v190, v165, v190
	v_lshlrev_b32_e64 v191, v191, 1
	v_cndmask_b32_e32 v190, v190, v166, vcc
	v_cndmask_b32_e64 v191, v191, 0, vcc
	ds_add_u32 v190, v191
	v_lshrrev_b32_e32 v190, 20, v187
	v_cmp_eq_u32_e32 vcc, 0, v187
	v_lshrrev_b32_e32 v191, 17, v187
	v_and_b32_e32 v190, 0xffc, v190
	v_and_b32_e32 v191, 16, v191
	v_add3_u32 v190, v165, v190, s73
	v_lshlrev_b32_e64 v191, v191, 1
	v_cndmask_b32_e32 v190, v190, v166, vcc
	v_cndmask_b32_e64 v191, v191, 0, vcc
	ds_add_u32 v190, v191
	s_branch .Lidx_postdone0
.Lidx_edge1:
	v_max_i32_e32 v177, 0, v20
	v_max_i32_e32 v176, 0, v28
	v_max_i32_e32 v179, 0, v21
	v_pk_fma_f32 v[176:177], v[134:135], v[176:177], 0 op_sel_hi:[1,1,0]
	v_max_i32_e32 v178, 0, v29
	v_max_i32_e32 v181, 0, v22
	v_max_i32_e32 v180, 0, v30
	v_pk_fma_f32 v[176:177], v[36:37], v[178:179], v[176:177]
	v_lshl_or_b32 v188, s14, 5, v164
	v_pk_fma_f32 v[176:177], v[136:137], v[180:181], v[176:177]
	v_max_i32_e32 v179, 0, v23
	v_max_i32_e32 v178, 0, v31
	v_pk_fma_f32 v[176:177], v[38:39], v[178:179], v[176:177]
	v_max_i32_e32 v179, 0, v24
	v_max_i32_e32 v178, 0, v32
	v_pk_fma_f32 v[176:177], v[138:139], v[178:179], v[176:177]
	v_max_i32_e32 v179, 0, v25
	v_max_i32_e32 v178, 0, v33
	v_pk_fma_f32 v[176:177], v[40:41], v[178:179], v[176:177]
	v_max_i32_e32 v179, 0, v26
	v_max_i32_e32 v178, 0, v34
	v_pk_fma_f32 v[176:177], v[140:141], v[178:179], v[176:177]
	v_max_i32_e32 v179, 0, v27
	v_max_i32_e32 v178, 0, v35
	v_pk_fma_f32 v[176:177], v[42:43], v[178:179], v[176:177]
	s_nop 0
	v_and_b32_e32 v183, 0x7fffffff, v177
	v_and_b32_e32 v182, 0x7fffffff, v176
	v_xor_b32_e32 v185, -1, v177
	v_pk_add_f32 v[182:183], v[182:183], 0 neg_lo:[1,1] neg_hi:[1,1]
	v_cmp_gt_i32_e32 vcc, 0, v177
	v_xor_b32_e32 v184, -1, v176
	s_nop 0
	v_cndmask_b32_e32 v186, v183, v185, vcc
	v_cmp_gt_i32_e32 vcc, 0, v176
	s_nop 1
	v_cndmask_b32_e32 v187, v182, v184, vcc
	v_cmp_le_i32_e32 vcc, v188, v132
	s_nop 1
	v_cndmask_b32_e32 v187, 0, v187, vcc
	v_cmp_le_i32_e32 vcc, v188, v1
	v_lshl_add_u32 v189, s14, 7, v175
	s_nop 0
	v_cndmask_b32_e32 v186, 0, v186, vcc
	ds_write2st64_b32 v189, v186, v187 offset1:128
	v_lshrrev_b32_e32 v190, 20, v186
	v_cmp_eq_u32_e32 vcc, 0, v186
	v_lshrrev_b32_e32 v191, 17, v186
	v_and_b32_e32 v190, 0xffc, v190
	v_and_b32_e32 v191, 16, v191
	v_add_u32_e32 v190, v165, v190
	v_lshlrev_b32_e64 v191, v191, 1
	v_cndmask_b32_e32 v190, v190, v166, vcc
	v_cndmask_b32_e64 v191, v191, 0, vcc
	ds_add_u32 v190, v191
	v_lshrrev_b32_e32 v190, 20, v187
	v_cmp_eq_u32_e32 vcc, 0, v187
	v_lshrrev_b32_e32 v191, 17, v187
	v_and_b32_e32 v190, 0xffc, v190
	v_and_b32_e32 v191, 16, v191
	v_add3_u32 v190, v165, v190, s73
	v_lshlrev_b32_e64 v191, v191, 1
	v_cndmask_b32_e32 v190, v190, v166, vcc
	v_cndmask_b32_e64 v191, v191, 0, vcc
	ds_add_u32 v190, v191
	s_branch .Lidx_postdone1

.LBB0_723:
	s_cmp_lt_i32 s53, 4
	s_cselect_b64 s[14:15], -1, 0
	s_cmp_gt_i32 s53, 3
	v_cmp_ne_u32_e64 s[6:7], 63, v145
	v_cmp_gt_u32_e32 vcc, 32, v145
	s_waitcnt lgkmcnt(0)
	s_barrier
	s_cbranch_scc1 .LBB0_729
	s_lshl_b32 s10, s53, 12
	s_add_i32 s10, s10, 0
	v_lshl_add_u32 v1, v145, 6, s10
	v_add_u32_e32 v1, 0x20000, v1
	ds_read_b128 v[4:7], v1
	ds_read_b128 v[8:11], v1 offset:16
	ds_read_b128 v[12:15], v1 offset:32
	ds_read_b128 v[16:19], v1 offset:48
	s_waitcnt lgkmcnt(3)
	v_add_u32_sdwa v1, v4, v4 dst_sel:DWORD dst_unused:UNUSED_PAD src0_sel:WORD_1 src1_sel:WORD_0
	v_and_b32_e32 v3, 0xffff, v5
	v_lshrrev_b32_e32 v4, 16, v5
	v_add3_u32 v1, v1, v4, v3
	v_and_b32_e32 v3, 0xffff, v6
	v_lshrrev_b32_e32 v4, 16, v6
	v_add3_u32 v1, v1, v4, v3
	v_and_b32_e32 v3, 0xffff, v7
	v_lshrrev_b32_e32 v4, 16, v7
	v_add3_u32 v1, v1, v4, v3
	s_waitcnt lgkmcnt(2)
	v_and_b32_e32 v3, 0xffff, v8
	v_lshrrev_b32_e32 v4, 16, v8
	v_add3_u32 v1, v1, v4, v3
	v_and_b32_e32 v3, 0xffff, v9
	v_lshrrev_b32_e32 v4, 16, v9
	v_add3_u32 v1, v1, v4, v3
	v_and_b32_e32 v3, 0xffff, v10
	v_lshrrev_b32_e32 v4, 16, v10
	v_add3_u32 v1, v1, v4, v3
	v_and_b32_e32 v3, 0xffff, v11
	v_lshrrev_b32_e32 v4, 16, v11
	v_add3_u32 v1, v1, v4, v3
	s_waitcnt lgkmcnt(1)
	v_and_b32_e32 v3, 0xffff, v12
	v_lshrrev_b32_e32 v4, 16, v12
	v_add3_u32 v1, v1, v4, v3
	v_and_b32_e32 v3, 0xffff, v13
	v_lshrrev_b32_e32 v4, 16, v13
	v_add3_u32 v1, v1, v4, v3
	v_and_b32_e32 v3, 0xffff, v14
	v_lshrrev_b32_e32 v4, 16, v14
	v_add3_u32 v1, v1, v4, v3
	v_and_b32_e32 v3, 0xffff, v15
	v_lshrrev_b32_e32 v4, 16, v15
	v_add3_u32 v1, v1, v4, v3
	s_waitcnt lgkmcnt(0)
	v_and_b32_e32 v3, 0xffff, v16
	v_lshrrev_b32_e32 v4, 16, v16
	v_add3_u32 v1, v1, v4, v3
	v_and_b32_e32 v3, 0xffff, v17
	v_lshrrev_b32_e32 v4, 16, v17
	v_add3_u32 v1, v1, v4, v3
	v_and_b32_e32 v3, 0xffff, v18
	v_lshrrev_b32_e32 v4, 16, v18
	v_and_b32_e32 v5, 63, v147
	v_add3_u32 v1, v1, v4, v3
	v_and_b32_e32 v3, 0xffff, v19
	v_lshrrev_b32_e32 v4, 16, v19
	v_cmp_ne_u32_e64 s[10:11], 63, v5
	v_add3_u32 v8, v1, v4, v3
	s_nop 0
	v_addc_co_u32_e64 v1, s[10:11], 0, v147, s[10:11]
	v_lshlrev_b32_e32 v1, 2, v1
	ds_bpermute_b32 v3, v1, v8
	s_waitcnt lgkmcnt(0)
	v_cndmask_b32_e64 v3, 0, v3, s[6:7]
	v_cmp_gt_u32_e64 s[6:7], 62, v5
	v_add_u32_e32 v4, v8, v3
	s_nop 0
	v_cndmask_b32_e64 v3, 0, 2, s[6:7]
	v_add_lshl_u32 v3, v3, v147, 2
	ds_bpermute_b32 v6, v3, v4
	v_cmp_gt_u32_e64 s[6:7], 62, v145
	s_waitcnt lgkmcnt(0)
	s_nop 0
	v_cndmask_b32_e64 v6, 0, v6, s[6:7]
	v_cmp_gt_u32_e64 s[6:7], 60, v5
	v_add_u32_e32 v6, v4, v6
	s_nop 0
	v_cndmask_b32_e64 v4, 0, 4, s[6:7]
	v_add_lshl_u32 v4, v4, v147, 2
	ds_bpermute_b32 v7, v4, v6
	v_cmp_gt_u32_e64 s[6:7], 60, v145
	s_waitcnt lgkmcnt(0)
	s_nop 0
	v_cndmask_b32_e64 v7, 0, v7, s[6:7]
	v_cmp_gt_u32_e64 s[6:7], 56, v5
	v_add_u32_e32 v7, v6, v7
	s_nop 0
	v_cndmask_b32_e64 v6, 0, 8, s[6:7]
	v_add_lshl_u32 v6, v6, v147, 2
	ds_bpermute_b32 v9, v6, v7
	v_cmp_gt_u32_e64 s[6:7], 56, v145
	s_waitcnt lgkmcnt(0)
	s_nop 0
	v_cndmask_b32_e64 v9, 0, v9, s[6:7]
	v_cmp_gt_u32_e64 s[6:7], 48, v5
	v_add_u32_e32 v9, v7, v9
	s_nop 0
	v_cndmask_b32_e64 v5, 0, 16, s[6:7]
	v_add_lshl_u32 v7, v5, v147, 2
	ds_bpermute_b32 v5, v7, v9
	s_lshl_b32 s6, s53, 5
	s_add_i32 s12, s6, 0
	v_cmp_gt_u32_e64 s[6:7], 48, v145
	s_waitcnt lgkmcnt(0)
	s_nop 0
	v_cndmask_b32_e64 v5, 0, v5, s[6:7]
	v_add_u32_e32 v9, v9, v5
	ds_bpermute_b32 v10, v153, v9
	s_add_i32 s6, s12, 0x25804
	v_mov_b32_e32 v5, s6
	ds_read_b32 v5, v5
	s_waitcnt lgkmcnt(1)
	v_cndmask_b32_e32 v10, 0, v10, vcc
	v_add_u32_e32 v9, v9, v10
	v_sub_u32_e32 v8, v9, v8
	s_waitcnt lgkmcnt(0)
	v_cmp_lt_u32_e64 s[6:7], v8, v5
	v_cmp_le_u32_e64 s[10:11], v5, v9
	s_and_b64 s[6:7], s[10:11], s[6:7]
	v_cndmask_b32_e64 v9, 0, 1, s[6:7]
	v_cmp_ne_u32_e64 s[6:7], 0, v9
	s_ff1_i32_b64 s10, s[6:7]
	s_cmp_lg_u64 s[6:7], 0
	s_cselect_b32 s16, s10, 0
	v_and_or_b32 v9, v147, 64, s16
	v_lshlrev_b32_e32 v9, 2, v9
	ds_bpermute_b32 v9, v9, v8
	v_cmp_lt_u32_e64 s[6:7], 31, v145
	v_mov_b32_e32 v8, 0
	s_and_saveexec_b64 s[10:11], vcc
	s_cbranch_execz .LBB0_726
	s_lshl_b32 s17, s53, 10
	s_lshl_b32 s18, s16, 6
	s_add_i32 s18, s18, 0
	s_lshl_b32 s17, s17, 2
	v_lshlrev_b32_e32 v8, 1, v145
	s_add_i32 s18, s18, s17
	v_and_b32_e32 v8, 0x7c, v8
	v_add_u32_e32 v8, s18, v8
	v_add_u32_e32 v8, 0x20000, v8
	ds_read_b32 v8, v8
	v_and_b32_e32 v10, 1, v144
	v_cmp_eq_u32_e32 vcc, 0, v10
	s_waitcnt lgkmcnt(0)
	s_nop 0
	v_cndmask_b32_sdwa v8, v8, v8, vcc dst_sel:DWORD dst_unused:UNUSED_PAD src0_sel:WORD_1 src1_sel:WORD_0

.LBB0_975:
	s_or_b64 exec, exec, s[4:5]
	v_mov_b32_e32 v15, v202
	s_add_u32 s62, s28, 0x14000000
	s_waitcnt lgkmcnt(0)
	s_barrier
	s_nop 0
	s_nop 0
	s_nop 0
	s_nop 0
	s_nop 0
	s_nop 0
	s_nop 0
	s_addc_u32 s63, s29, 0
	v_readfirstlane_b32 s4, v15
	s_ashr_i32 s4, s4, 6
	s_and_b64 s[6:7], s[46:47], exec
	s_cselect_b32 s5, 8, 1
	v_cvt_f32_ubyte0_e32 v1, s5
	v_rcp_iflag_f32_e32 v1, v1
	s_add_i32 s8, s5, -1
	s_and_b64 s[6:7], s[46:47], exec
	s_cselect_b32 s24, 3, 0
	v_mul_f32_e32 v1, 0x4f7ffffe, v1
	v_cvt_u32_f32_e32 v1, v1
	s_sub_i32 s9, 0, s5
	s_abs_i32 s7, s30
	s_lshr_b32 s6, s2, s24
	v_readfirstlane_b32 s10, v1
	s_mul_i32 s9, s9, s10
	s_mul_hi_u32 s9, s10, s9
	s_add_i32 s10, s10, s9
	s_mul_hi_u32 s9, s7, s10
	s_mul_i32 s10, s9, s5
	s_sub_i32 s7, s7, s10
	s_lshl_b32 s6, s6, 3
	s_ashr_i32 s68, s30, 31
	s_add_i32 s10, s9, 1
	s_sub_i32 s11, s7, s5
	s_cmp_ge_u32 s7, s5
	s_cselect_b32 s9, s10, s9
	s_cselect_b32 s7, s11, s7
	s_add_i32 s10, s9, 1
	s_cmp_ge_u32 s7, s5
	s_cselect_b32 s7, s10, s9
	s_xor_b32 s7, s7, s68
	s_sub_i32 s7, s7, s68
	s_lshl_b32 s25, s7, 3
	s_abs_i32 s7, s25
	v_cvt_f32_u32_e32 v1, s7
	s_add_i32 s40, s4, s6
	s_sub_i32 s6, s25, s40
	s_and_b32 s41, s8, s2
	v_rcp_iflag_f32_e32 v1, v1
	s_add_i32 s8, s6, 0x1fff
	s_sub_i32 s6, 0xffffe001, s6
	s_xor_b32 s9, s8, s25
	v_mul_f32_e32 v1, 0x4f7ffffe, v1
	v_cvt_u32_f32_e32 v1, v1
	s_max_i32 s6, s8, s6
	s_sub_i32 s8, 0, s7
	s_ashr_i32 s9, s9, 31
	v_readfirstlane_b32 s10, v1
	s_mul_i32 s8, s8, s10
	s_mul_hi_u32 s8, s10, s8
	s_add_i32 s10, s10, s8
	s_mul_hi_u32 s8, s6, s10
	s_mul_i32 s10, s8, s7
	s_sub_i32 s6, s6, s10
	s_add_i32 s10, s8, 1
	s_sub_i32 s11, s6, s7
	s_cmp_ge_u32 s6, s7
	s_cselect_b32 s8, s10, s8
	s_cselect_b32 s6, s11, s6
	s_add_i32 s10, s8, 1
	s_cmp_ge_u32 s6, s7
	s_cselect_b32 s6, s10, s8
	s_sub_i32 s5, s5, s41
	s_xor_b32 s6, s6, s9
	s_add_i32 s5, s5, 15
	s_sub_i32 s42, s6, s9
	s_lshr_b32 s5, s5, s24
	s_mul_i32 s43, s42, s5
	s_cmp_lt_i32 s43, 1
	s_mov_b32 s9, 0
	s_cbranch_scc1 .LBB0_980
	s_lshl_b32 s5, s4, 14
	s_lshl_b32 s4, s4, 10
	s_add_i32 s47, s4, 0
	s_lshr_b32 s8, s41, 2
	s_add_i32 s46, s5, 0
	s_add_i32 s47, s47, 0x20000
	s_and_b32 s10, s41, 3
	s_lshl_b64 s[4:5], s[8:9], 13
	s_ashr_i32 s6, s40, 31
	s_add_u32 s4, s4, s40
	s_addc_u32 s5, s5, s6
	s_lshl_b64 s[6:7], s[4:5], 9
	v_and_b32_e32 v14, 63, v15
	s_add_u32 s6, s44, s6
	s_addc_u32 s7, s45, s7
	v_lshlrev_b32_e32 v42, 3, v14
	global_load_dwordx2 v[2:3], v42, s[6:7]
	v_and_b32_e32 v17, 15, v15
	v_bfe_u32 v4, v15, 4, 2
	v_bfe_u32 v6, v15, 2, 2
	v_and_b32_e32 v1, 7, v15
	v_lshlrev_b32_e32 v34, 3, v15
	v_mov_b32_e32 v7, 0x1000
	v_lshrrev_b32_e32 v9, 3, v15
	v_or_b32_e32 v12, 16, v17
	v_lshl_or_b32 v6, v4, 2, v6
	v_bfe_u32 v5, v15, 3, 1
	v_and_b32_e32 v10, 1, v15
	v_bitop3_b32 v13, v4, v1, 4 bitop3:0x36
	v_bitop3_b32 v16, v4, v15, 7 bitop3:0x78
	v_and_or_b32 v7, v34, 24, v7
	v_xor_b32_e32 v9, v9, v15
	v_mul_u32_u24_e32 v21, 0x40004, v14
	v_lshrrev_b32_e32 v22, 3, v12
	v_lshlrev_b32_e32 v24, 4, v6
	v_lshlrev_b32_e32 v6, 7, v6
	s_cmpk_gt_i32 s40, 0xff
	s_movk_i32 s6, 0x60
	v_lshlrev_b32_e32 v12, 7, v12
	v_xor_b32_e32 v23, v13, v5
	v_xor_b32_e32 v5, v16, v5
	v_and_or_b32 v9, v9, 6, v10
	v_or_b32_e32 v60, 0x10000, v21
	v_or_b32_e32 v61, 0x30002, v21
	v_xor_b32_e32 v10, v13, v22
	v_xor_b32_e32 v13, v16, v22
	v_or_b32_e32 v16, 0x800, v6
	v_or_b32_e32 v6, v6, v7
	s_cselect_b64 vcc, -1, 0
	v_lshlrev_b32_e32 v11, 6, v15
	s_waitcnt vmcnt(2)
	v_lshlrev_b32_e32 v52, 4, v9
	v_add_u32_e32 v9, s47, v42
	v_lshl_or_b32 v37, v10, 4, v12
	v_bitop3_b32 v10, v24, v16, s6 bitop3:0xce
	v_bitop3_b32 v39, v24, v6, s6 bitop3:0xce
	s_mul_hi_u32 s6, s4, 0x1200
	s_mulk_i32 s5, 0x1200
	s_mulk_i32 s4, 0x1200
	s_add_i32 s6, s6, s5
	v_mov_b32_e32 v43, 0
	s_add_u32 s4, s38, s4
	v_mov_b32_e32 v8, 0x60
	v_lshlrev_b32_e32 v19, 7, v17
	s_addc_u32 s5, s39, s6
	v_lshl_or_b32 v35, v23, 4, v19
	v_lshl_or_b32 v36, v5, 4, v19
	v_and_b32_e32 v5, 0x60, v24
	v_bitop3_b32 v19, v24, 64, v8 bitop3:0x6c
	v_bitop3_b32 v8, v24, 32, v8 bitop3:0x6c
	v_bfe_u32 v18, v15, 3, 3
	v_lshl_or_b32 v38, v13, 4, v12
	v_or_b32_e32 v12, v19, v16
	v_or_b32_e32 v13, v8, v16
	v_or_b32_e32 v41, v8, v6
	v_or_b32_e32 v8, v5, v16
	s_waitcnt vmcnt(1)
	v_or_b32_e32 v56, v6, v5
	v_lshlrev_b32_e32 v16, 3, v4
	v_and_b32_e32 v4, 48, v15
	v_mov_b32_e32 v5, v43
	v_lshlrev_b32_e32 v63, 6, v18
	v_bitop3_b32 v20, v18, v15, 7 bitop3:0x78
	v_or_b32_e32 v40, v19, v6
	v_add_u32_e32 v57, v10, v7
	v_add_u32_e32 v58, v12, v7
	v_add_u32_e32 v59, v13, v7
	v_add_u32_e32 v90, v8, v7
	v_add_u32_e32 v18, s47, v63
	v_mov_b32_e32 v19, v43
	v_lshlrev_b32_e32 v44, 4, v20
	v_mov_b32_e32 v45, v43
	s_mov_b32 m0, s46
	v_mov_b32_e32 v53, v43
	v_mov_b32_e32 v64, 9
	v_xor_b32_e32 v50, 16, v44
	v_mov_b32_e32 v51, v43
	v_xor_b32_e32 v48, 32, v44
	s_waitcnt vmcnt(0)
	v_cndmask_b32_e32 v2, v60, v2, vcc
	v_cndmask_b32_e32 v3, v61, v3, vcc
	ds_write_b64 v9, v[2:3]
	v_and_b32_e32 v2, 0xc0, v11
	v_lshlrev_b32_e32 v62, 1, v2
	v_lshl_or_b32 v2, s10, 9, v62
	v_mov_b32_e32 v3, v43
	v_lshl_add_u64 v[2:3], s[4:5], 0, v[2:3]
	s_lshl_b64 s[4:5], s[8:9], 22
	s_add_u32 s6, s80, s4
	v_lshl_add_u64 v[2:3], v[2:3], 0, v[4:5]
	s_addc_u32 s7, s81, s5
	global_load_dwordx4 v[10:13], v[2:3], off
	global_load_dwordx4 v[6:9], v[2:3], off offset:64
	s_waitcnt lgkmcnt(0)
	s_add_u32 s4, s37, s4
	ds_read_b128 v[30:33], v18
	ds_read_b128 v[22:25], v18 offset:16
	ds_read_b128 v[2:5], v18 offset:32
	ds_read_b128 v[26:29], v18 offset:48
	s_addc_u32 s5, s79, s5
	s_lshl_b32 s8, s10, 7
	s_add_u32 s4, s4, s8
	s_addc_u32 s5, s5, 0
	s_waitcnt lgkmcnt(3)
	v_lshlrev_b32_e32 v18, 9, v30
	s_add_u32 s6, s6, s8
	v_and_b32_e32 v18, 0x1fffe00, v18
	s_addc_u32 s7, s7, 0
	v_lshl_add_u64 v[20:21], s[4:5], 0, v[18:19]
	s_add_i32 s48, s46, 0x1000
	v_lshl_add_u64 v[20:21], v[20:21], 0, v[44:45]
	v_lshl_add_u64 v[18:19], s[6:7], 0, v[18:19]
	global_load_lds_dwordx4 v[20:21], off
	v_lshl_add_u64 v[18:19], v[18:19], 0, v[52:53]
	s_mov_b32 m0, s48
	s_add_i32 s49, s46, 0x400
	global_load_lds_dwordx4 v[18:19], off
	v_lshlrev_b32_sdwa v18, v64, v30 dst_sel:DWORD dst_unused:UNUSED_PAD src0_sel:DWORD src1_sel:WORD_1
	v_mov_b32_e32 v19, v43
	v_lshl_add_u64 v[20:21], s[4:5], 0, v[18:19]
	v_lshl_add_u64 v[20:21], v[20:21], 0, v[50:51]
	s_mov_b32 m0, s49
	v_lshl_add_u64 v[18:19], s[6:7], 0, v[18:19]
	s_add_i32 s50, s46, 0x1400
	global_load_lds_dwordx4 v[20:21], off
	v_lshl_add_u64 v[18:19], v[18:19], 0, v[52:53]
	s_mov_b32 m0, s50
	v_mov_b32_e32 v49, v43
	global_load_lds_dwordx4 v[18:19], off
	v_lshlrev_b32_e32 v18, 9, v31
	v_and_b32_e32 v18, 0x1fffe00, v18
	v_mov_b32_e32 v19, v43
	v_lshl_add_u64 v[20:21], s[4:5], 0, v[18:19]
	s_add_i32 s51, s46, 0x800
	v_lshl_add_u64 v[20:21], v[20:21], 0, v[48:49]
	s_mov_b32 m0, s51
	v_lshl_add_u64 v[18:19], s[6:7], 0, v[18:19]
	s_add_i32 s52, s46, 0x1800
	global_load_lds_dwordx4 v[20:21], off
	v_lshl_add_u64 v[18:19], v[18:19], 0, v[52:53]
	s_mov_b32 m0, s52
	v_xor_b32_e32 v46, 48, v44
	global_load_lds_dwordx4 v[18:19], off
	v_lshlrev_b32_sdwa v18, v64, v31 dst_sel:DWORD dst_unused:UNUSED_PAD src0_sel:DWORD src1_sel:WORD_1
	v_mov_b32_e32 v19, v43
	v_lshl_add_u64 v[20:21], s[4:5], 0, v[18:19]
	v_mov_b32_e32 v47, v43
	s_add_i32 s53, s46, 0xc00
	v_lshl_add_u64 v[20:21], v[20:21], 0, v[46:47]
	s_mov_b32 m0, s53
	v_lshl_add_u64 v[18:19], s[6:7], 0, v[18:19]
	s_add_i32 s54, s46, 0x1c00
	global_load_lds_dwordx4 v[20:21], off
	v_lshl_add_u64 v[18:19], v[18:19], 0, v[52:53]
	s_mov_b32 m0, s54
	v_cmp_gt_u32_e64 s[4:5], 4, v17
	global_load_lds_dwordx4 v[18:19], off
	v_and_b32_e32 v17, 0x80, v34
	v_bfe_u32 v15, v15, 5, 1
	v_or_b32_e32 v19, 32, v17
	v_or_b32_e32 v20, 64, v17
	v_or_b32_e32 v21, 0x60, v17
	v_or_b32_e32 v30, 6, v15
	v_or_b32_e32 v82, v17, v30
	v_or_b32_e32 v84, v19, v30
	v_or_b32_e32 v86, v20, v30
	v_or_b32_e32 v88, v21, v30
	v_or_b32_e32 v30, 10, v15
	v_or_b32_e32 v18, 2, v15
	v_or_b32_e32 v98, v17, v30
	v_or_b32_e32 v100, v19, v30
	v_or_b32_e32 v102, v20, v30
	v_or_b32_e32 v104, v21, v30
	v_or_b32_e32 v30, 14, v15
	v_or_b32_e32 v66, v17, v18
	v_or_b32_e32 v68, v19, v18
	v_or_b32_e32 v70, v20, v18
	v_or_b32_e32 v72, v21, v18
	v_or_b32_e32 v18, 4, v15
	v_or_b32_e32 v106, v17, v30
	v_or_b32_e32 v108, v19, v30
	v_or_b32_e32 v110, v20, v30
	v_or_b32_e32 v112, v21, v30
	v_or_b32_e32 v30, 18, v15
	v_or_b32_e32 v81, v17, v18
	v_or_b32_e32 v83, v19, v18
	v_or_b32_e32 v85, v20, v18
	v_or_b32_e32 v87, v21, v18
	v_or_b32_e32 v18, 8, v15
	v_or_b32_e32 v114, v17, v30
	v_or_b32_e32 v116, v19, v30
	v_or_b32_e32 v118, v20, v30
	v_or_b32_e32 v120, v21, v30
	v_or_b32_e32 v30, 22, v15
	v_lshl_add_u64 v[54:55], s[44:45], 0, v[42:43]
	v_or_b32_e32 v97, v17, v18
	v_or_b32_e32 v99, v19, v18
	v_or_b32_e32 v101, v20, v18
	v_or_b32_e32 v103, v21, v18
	v_or_b32_e32 v18, 12, v15
	v_or_b32_e32 v122, v17, v30
	v_or_b32_e32 v124, v19, v30
	v_or_b32_e32 v126, v20, v30
	v_or_b32_e32 v128, v21, v30
	v_or_b32_e32 v30, 26, v15
	s_abs_i32 s45, s42
	v_or_b32_e32 v105, v17, v18
	v_or_b32_e32 v107, v19, v18
	v_or_b32_e32 v109, v20, v18
	v_or_b32_e32 v111, v21, v18
	v_or_b32_e32 v18, 16, v15
	v_or_b32_e32 v130, v17, v30
	v_or_b32_e32 v132, v19, v30
	v_or_b32_e32 v134, v20, v30
	v_or_b32_e32 v136, v21, v30
	v_cvt_f32_u32_e32 v30, s45
	v_or_b32_e32 v113, v17, v18
	v_or_b32_e32 v115, v19, v18
	v_or_b32_e32 v117, v20, v18
	v_or_b32_e32 v119, v21, v18
	v_or_b32_e32 v18, 20, v15
	v_or_b32_e32 v121, v17, v18
	v_or_b32_e32 v123, v19, v18
	v_or_b32_e32 v125, v20, v18
	v_or_b32_e32 v127, v21, v18
	v_or_b32_e32 v18, 24, v15
	v_or_b32_e32 v65, v17, v15
	v_or_b32_e32 v67, v19, v15
	v_or_b32_e32 v69, v20, v15
	v_or_b32_e32 v71, v21, v15
	v_or_b32_e32 v129, v17, v18
	v_or_b32_e32 v131, v19, v18
	v_or_b32_e32 v133, v20, v18
	v_or_b32_e32 v135, v21, v18
	v_or_b32_e32 v18, 28, v15
	v_or_b32_e32 v15, 30, v15
	v_or_b32_e32 v137, v17, v18
	v_or_b32_e32 v138, v17, v15
	v_rcp_iflag_f32_e32 v17, v30
	s_sub_i32 s8, 0, s45
	s_add_i32 s44, s46, 0x2000
	v_lshlrev_b32_e32 v1, 2, v14
	v_mul_f32_e32 v17, 0x4f7ffffe, v17
	v_cvt_u32_f32_e32 v17, v17
	s_waitcnt vmcnt(0)
	v_cndmask_b32_e64 v9, 0, v9, s[4:5]
	v_cndmask_b32_e64 v8, 0, v8, s[4:5]
	v_cndmask_b32_e64 v7, 0, v7, s[4:5]
	v_readfirstlane_b32 s10, v17
	s_mul_i32 s8, s8, s10
	s_mul_hi_u32 s8, s10, s8
	v_cndmask_b32_e64 v6, 0, v6, s[4:5]
	v_cndmask_b32_e64 v13, 0, v13, s[4:5]
	v_cndmask_b32_e64 v12, 0, v12, s[4:5]
	v_cndmask_b32_e64 v11, 0, v11, s[4:5]
	v_cndmask_b32_e64 v10, 0, v10, s[4:5]
	v_cmp_gt_u32_e64 s[6:7], 16, v14
	v_add_u32_e32 v73, s46, v56
	v_add_u32_e32 v74, s46, v90
	v_add_u32_e32 v75, s46, v41
	v_add_u32_e32 v76, s46, v59
	v_add_u32_e32 v77, s46, v40
	v_add_u32_e32 v78, s46, v58
	v_add_u32_e32 v79, s46, v39
	v_add_u32_e32 v80, s46, v57
	v_add_u32_e32 v89, s44, v56
	v_add_u32_e32 v90, s44, v90
	v_add_u32_e32 v91, s44, v41
	v_add_u32_e32 v92, s44, v59
	v_add_u32_e32 v93, s44, v40
	v_add_u32_e32 v94, s44, v58
	v_add_u32_e32 v95, s44, v39
	v_add_u32_e32 v96, s44, v57
	v_or_b32_e32 v139, v19, v18
	v_or_b32_e32 v140, v19, v15
	v_or_b32_e32 v141, v20, v18
	v_or_b32_e32 v142, v20, v15
	v_or_b32_e32 v143, v21, v18
	v_or_b32_e32 v144, v21, v15
	s_ashr_i32 s55, s42, 31
	s_add_i32 s56, s10, s8
	s_sub_i32 s57, 0, s42
	v_lshlrev_b32_e32 v56, 1, v16
	s_add_i32 s58, s46, 0x3000
	s_add_i32 s59, s46, 0x2400
	s_add_i32 s60, s46, 0x3400
	s_add_i32 s61, s46, 0x2800
	s_add_i32 s64, s46, 0x3800
	s_add_i32 s65, s46, 0x2c00
	s_add_i32 s66, s46, 0x3c00
	v_add_u32_e32 v145, s46, v36
	v_add_u32_e32 v149, s46, v35
	v_add_u32_e32 v151, s46, v38
	v_add_u32_e32 v153, s46, v37
	v_lshlrev_b32_e32 v58, 1, v14
	s_movk_i32 s67, 0x7fff
	s_mov_b32 s69, 0
	s_mov_b32 s70, 0
	s_branch .LBB0_978
